# pv half of the expert-table quantization moved from P7 to the end of P6 on the even-slot workgroups (idle there while the delayed half finishes); P7 has no table work left
# speedup vs baseline: 1.0211x; 1.0076x over previous
; DI void phase7(const Params& P, char* smem) {
;     ...
;   for (int row = VB * 4 + wid; row < 2 * 16384; row += NVB * 4) {
;     const bool isv = row >= 16384; const int e = row & 16383;
;     const float* src = (isv ? P.pv : P.pu) + (long)e * 1024 + lane * 16;
;     float f[16];
; #pragma unroll
;     for (int k = 0; k < 4; ++k) { const float4 a = reinterpret_cast<const float4*>(src)[k]; f[4 * k] = a.x; f[4 * k + 1] = a.y; f[4 * k + 2] = a.z; f[4 * k + 3] = a.w; }
;     float am = 0.f;
; #pragma unroll
;     for (int k = 0; k < 16; ++k) am = fmaxf(am, fabsf(f[k]));
;     am = wave_max(am);
;     const float inv = am > 0.f ? 127.f / am : 0.f;
;     unsigned w[4];
; #pragma unroll
;     for (int k = 0; k < 4; ++k) {
;       unsigned pk = 0;
; #pragma unroll
;       for (int b = 0; b < 4; ++b) { int q = (int)rintf(f[4 * k + b] * inv); q = q > 127 ? 127 : (q < -127 ? -127 : q); pk |= ((unsigned)((isv ? q + 128 : q) & 0xff)) << (8 * b); }
;       w[k] = pk;
;     }
;     *reinterpret_cast<uint4*>(ws + (isv ? OFF_VQ + ((long)(lane >> 3) * 16384 + e) * 128 + (lane & 7) * 16 : OFF_UQ + (long)e * 1024 + lane * 16)) = make_uint4(w[0], w[1], w[2], w[3]);
;     if (lane == 0) reinterpret_cast<float*>(ws + (isv ? OFF_VS : OFF_US))[e] = am * (1.f / 127.f);
;   }
.LBB0_949:
	s_bitcmp1_b32 s74, 3
	s_cbranch_scc1 .Lp6u_skip
	s_mov_b64 s[26:27], s[16:17]
	s_mov_b64 s[28:29], s[18:19]
	s_mov_b64 s[30:31], s[20:21]
	s_mov_b64 s[34:35], exec
	v_readlane_b32 s12, v254, 8
	v_lshlrev_b32_e32 v16, 4, v208
	v_cmp_eq_u32_e64 s[6:7], 0, v208
	v_and_b32_e32 v0, 12, v172
	v_lshl_add_u32 v0, s74, 3, v0
	v_or_b32_e32 v210, v0, v194
	s_lshl_b32 s12, s12, 3
	v_lshlrev_b32_e32 v0, 11, v189
	v_readlane_b32 s16, v254, 0
	v_mov_b32_e32 v19, 0
	v_and_b32_e32 v17, 0x1c000, v0
	v_and_b32_e32 v0, 0x70, v209
	v_readlane_b32 s17, v254, 1
	v_readlane_b32 s18, v254, 2
	v_readlane_b32 s19, v254, 3
	v_or_b32_e32 v24, 0x1000000, v0
	s_mov_b64 s[14:15], 0
	s_movk_i32 s2, 0x4000
	s_movk_i32 s4, 0x3fff
	v_mov_b32_e32 v25, s17
	v_mov_b32_e32 v26, s19
	v_mov_b32_e32 v27, s16
	v_mov_b32_e32 v28, s18
	v_lshlrev_b32_e32 v20, 2, v16
	v_mov_b32_e32 v21, v19
	s_mov_b32 s5, 0x42fe0000
	s_movk_i32 s13, 0xff81
	s_movk_i32 s16, 0xff
	s_movk_i32 s17, 0x7fff
	v_mov_b32_e32 v29, 0x7f
	v_add_u32_e32 v30, 0x4000, v210
	v_readlane_b32 s20, v254, 4
	v_readlane_b32 s21, v254, 5
	v_readlane_b32 s22, v254, 6
	v_readlane_b32 s23, v254, 7
	v_mov_b32_e32 v148, v30
	v_and_b32_e32 v149, 0x3fff, v148
	v_cmp_lt_i32_e64 s[32:33], s4, v148
	v_lshlrev_b32_e32 v150, 12, v149
	v_mov_b32_e32 v151, 0
	s_nop 0
	v_cndmask_b32_e64 v153, v25, v26, s[32:33]
	v_cndmask_b32_e64 v152, v27, v28, s[32:33]
	v_lshl_add_u64 v[152:153], v[152:153], 0, v[150:151]
	v_lshl_add_u64 v[152:153], v[152:153], 0, v[20:21]
	global_load_dwordx4 v[132:135], v[152:153], off
	global_load_dwordx4 v[136:139], v[152:153], off offset:16
	global_load_dwordx4 v[140:143], v[152:153], off offset:32
	global_load_dwordx4 v[144:147], v[152:153], off offset:48
	s_waitcnt vmcnt(0)
	s_branch .Lp6u1_loop

; DI void phase7(const Params& P, char* smem) {
;     ...
;   for (int row = VB * 4 + wid; row < 2 * 16384; row += NVB * 4) {
;     const bool isv = row >= 16384; const int e = row & 16383;
;     const float* src = (isv ? P.pv : P.pu) + (long)e * 1024 + lane * 16;
;     float f[16];
; #pragma unroll
;     for (int k = 0; k < 4; ++k) { const float4 a = reinterpret_cast<const float4*>(src)[k]; f[4 * k] = a.x; f[4 * k + 1] = a.y; f[4 * k + 2] = a.z; f[4 * k + 3] = a.w; }
;     float am = 0.f;
; #pragma unroll
;     for (int k = 0; k < 16; ++k) am = fmaxf(am, fabsf(f[k]));
;     am = wave_max(am);
;     const float inv = am > 0.f ? 127.f / am : 0.f;
;     unsigned w[4];
; #pragma unroll
;     for (int k = 0; k < 4; ++k) {
;       unsigned pk = 0;
; #pragma unroll
;       for (int b = 0; b < 4; ++b) { int q = (int)rintf(f[4 * k + b] * inv); q = q > 127 ? 127 : (q < -127 ? -127 : q); pk |= ((unsigned)((isv ? q + 128 : q) & 0xff)) << (8 * b); }
;       w[k] = pk;
;     }
;     *reinterpret_cast<uint4*>(ws + (isv ? OFF_VQ + ((long)(lane >> 3) * 16384 + e) * 128 + (lane & 7) * 16 : OFF_UQ + (long)e * 1024 + lane * 16)) = make_uint4(w[0], w[1], w[2], w[3]);
;     if (lane == 0) reinterpret_cast<float*>(ws + (isv ? OFF_VS : OFF_US))[e] = am * (1.f / 127.f);
;   }
.Lp6u1_done:
	s_mov_b64 exec, s[34:35]
	s_waitcnt vmcnt(0)
	v_add_u32_e32 v210, 64, v210
	v_lshlrev_b32_e32 v0, 11, v189
	v_readlane_b32 s16, v254, 0
	v_mov_b32_e32 v19, 0
	v_and_b32_e32 v17, 0x1c000, v0
	v_and_b32_e32 v0, 0x70, v209
	v_readlane_b32 s17, v254, 1
	v_readlane_b32 s18, v254, 2
	v_readlane_b32 s19, v254, 3
	v_or_b32_e32 v24, 0x1000000, v0
	s_mov_b64 s[14:15], 0
	s_movk_i32 s2, 0x4000
	s_movk_i32 s4, 0x3fff
	v_mov_b32_e32 v25, s17
	v_mov_b32_e32 v26, s19
	v_mov_b32_e32 v27, s16
	v_mov_b32_e32 v28, s18
	v_lshlrev_b32_e32 v20, 2, v16
	v_mov_b32_e32 v21, v19
	s_mov_b32 s5, 0x42fe0000
	s_movk_i32 s13, 0xff81
	s_movk_i32 s16, 0xff
	s_movk_i32 s17, 0x7fff
	v_mov_b32_e32 v29, 0x7f
	v_add_u32_e32 v30, 0x4000, v210
	v_readlane_b32 s20, v254, 4
	v_readlane_b32 s21, v254, 5
	v_readlane_b32 s22, v254, 6
	v_readlane_b32 s23, v254, 7
	v_mov_b32_e32 v148, v30
	v_and_b32_e32 v149, 0x3fff, v148
	v_cmp_lt_i32_e64 s[32:33], s4, v148
	v_lshlrev_b32_e32 v150, 12, v149
	v_mov_b32_e32 v151, 0
	s_nop 0
	v_cndmask_b32_e64 v153, v25, v26, s[32:33]
	v_cndmask_b32_e64 v152, v27, v28, s[32:33]
	v_lshl_add_u64 v[152:153], v[152:153], 0, v[150:151]
	v_lshl_add_u64 v[152:153], v[152:153], 0, v[20:21]
	global_load_dwordx4 v[132:135], v[152:153], off
	global_load_dwordx4 v[136:139], v[152:153], off offset:16
	global_load_dwordx4 v[140:143], v[152:153], off offset:32
	global_load_dwordx4 v[144:147], v[152:153], off offset:48
	s_waitcnt vmcnt(0)
	s_branch .Lp6u2_loop

; DI void phase7(const Params& P, char* smem) {
;     ...
;   for (int row = VB * 4 + wid; row < 2 * 16384; row += NVB * 4) {
;     const bool isv = row >= 16384; const int e = row & 16383;
;     const float* src = (isv ? P.pv : P.pu) + (long)e * 1024 + lane * 16;
;     float f[16];
; #pragma unroll
;     for (int k = 0; k < 4; ++k) { const float4 a = reinterpret_cast<const float4*>(src)[k]; f[4 * k] = a.x; f[4 * k + 1] = a.y; f[4 * k + 2] = a.z; f[4 * k + 3] = a.w; }
;     float am = 0.f;
; #pragma unroll
;     for (int k = 0; k < 16; ++k) am = fmaxf(am, fabsf(f[k]));
;     am = wave_max(am);
;     const float inv = am > 0.f ? 127.f / am : 0.f;
;     unsigned w[4];
; #pragma unroll
;     for (int k = 0; k < 4; ++k) {
;       unsigned pk = 0;
; #pragma unroll
;       for (int b = 0; b < 4; ++b) { int q = (int)rintf(f[4 * k + b] * inv); q = q > 127 ? 127 : (q < -127 ? -127 : q); pk |= ((unsigned)((isv ? q + 128 : q) & 0xff)) << (8 * b); }
;       w[k] = pk;
;     }
;     *reinterpret_cast<uint4*>(ws + (isv ? OFF_VQ + ((long)(lane >> 3) * 16384 + e) * 128 + (lane & 7) * 16 : OFF_UQ + (long)e * 1024 + lane * 16)) = make_uint4(w[0], w[1], w[2], w[3]);
;     if (lane == 0) reinterpret_cast<float*>(ws + (isv ? OFF_VS : OFF_US))[e] = am * (1.f / 127.f);
;   }
.Lp6u2_done:
	s_mov_b64 exec, s[34:35]
	s_waitcnt vmcnt(0)
	s_mov_b64 s[16:17], s[26:27]
	s_mov_b64 s[18:19], s[28:29]
	s_mov_b64 s[20:21], s[30:31]

; DI void phase7(const Params& P, char* smem) {
;     ...
;   for (int row = VB * 4 + wid; row < 2 * 16384; row += NVB * 4) {
;     const bool isv = row >= 16384; const int e = row & 16383;
;     const float* src = (isv ? P.pv : P.pu) + (long)e * 1024 + lane * 16;
;     float f[16];
; #pragma unroll
;     for (int k = 0; k < 4; ++k) { const float4 a = reinterpret_cast<const float4*>(src)[k]; f[4 * k] = a.x; f[4 * k + 1] = a.y; f[4 * k + 2] = a.z; f[4 * k + 3] = a.w; }
;     float am = 0.f;
; #pragma unroll
;     for (int k = 0; k < 16; ++k) am = fmaxf(am, fabsf(f[k]));
;     am = wave_max(am);
;     const float inv = am > 0.f ? 127.f / am : 0.f;
;     unsigned w[4];
; #pragma unroll
;     for (int k = 0; k < 4; ++k) {
;       unsigned pk = 0;
; #pragma unroll
;       for (int b = 0; b < 4; ++b) { int q = (int)rintf(f[4 * k + b] * inv); q = q > 127 ? 127 : (q < -127 ? -127 : q); pk |= ((unsigned)((isv ? q + 128 : q) & 0xff)) << (8 * b); }
;       w[k] = pk;
;     }
;     *reinterpret_cast<uint4*>(ws + (isv ? OFF_VQ + ((long)(lane >> 3) * 16384 + e) * 128 + (lane & 7) * 16 : OFF_UQ + (long)e * 1024 + lane * 16)) = make_uint4(w[0], w[1], w[2], w[3]);
;     if (lane == 0) reinterpret_cast<float*>(ws + (isv ? OFF_VS : OFF_US))[e] = am * (1.f / 127.f);
;   }
.LBB0_1006:
	s_or_b64 exec, exec, s[20:21]
	s_branch .LBB0_1014
	v_lshlrev_b32_e32 v0, 11, v189
	v_readlane_b32 s16, v254, 0
	v_mov_b32_e32 v19, 0
	v_and_b32_e32 v17, 0x1c000, v0
	v_and_b32_e32 v0, 0x70, v209
	v_readlane_b32 s17, v254, 1
	v_readlane_b32 s18, v254, 2
	v_readlane_b32 s19, v254, 3
	v_or_b32_e32 v24, 0x1000000, v0
	s_mov_b64 s[14:15], 0
	s_movk_i32 s2, 0x4000
	s_movk_i32 s4, 0x3fff
	v_mov_b32_e32 v25, s17
	v_mov_b32_e32 v26, s19
	v_mov_b32_e32 v27, s16
	v_mov_b32_e32 v28, s18
	v_lshlrev_b32_e32 v20, 2, v16
	v_mov_b32_e32 v21, v19
	s_mov_b32 s5, 0x42fe0000
	s_movk_i32 s13, 0xff81
	s_movk_i32 s16, 0xff
	s_movk_i32 s17, 0x7fff
	v_mov_b32_e32 v29, 0x7f
	v_add_u32_e32 v30, 0x4000, v210
	v_readlane_b32 s20, v254, 4
	v_readlane_b32 s21, v254, 5
	v_readlane_b32 s22, v254, 6
	v_readlane_b32 s23, v254, 7
	v_mov_b32_e32 v148, v30
	v_and_b32_e32 v149, 0x3fff, v148
	v_cmp_lt_i32_e64 s[32:33], s4, v148
	v_lshlrev_b32_e32 v150, 12, v149
	v_mov_b32_e32 v151, 0
	s_nop 0
	v_cndmask_b32_e64 v153, v25, v26, s[32:33]
	v_cndmask_b32_e64 v152, v27, v28, s[32:33]
	v_lshl_add_u64 v[152:153], v[152:153], 0, v[150:151]
	v_lshl_add_u64 v[152:153], v[152:153], 0, v[20:21]
	global_load_dwordx4 v[132:135], v[152:153], off
	global_load_dwordx4 v[136:139], v[152:153], off offset:16
	global_load_dwordx4 v[140:143], v[152:153], off offset:32
	global_load_dwordx4 v[144:147], v[152:153], off offset:48
	s_waitcnt vmcnt(0)
	s_branch .LBB0_1008
